# attention softmax: uniform fast path when running max unchanged + persistent -m*C register
# baseline (speedup 1.0000x reference)
.LBB0_509:
	s_xor_b64 s[18:19], s[4:5], -1
	s_lshl_b64 s[4:5], s[0:1], 1
	s_add_u32 s22, s56, s4
	s_addc_u32 s23, s57, s5
	v_mov_b32_e32 v2, v208
	s_add_u32 s0, s58, s4
	s_addc_u32 s1, s59, s5
	v_readfirstlane_b32 s20, v2
	s_ashr_i32 s24, s20, 6
	s_and_b32 s20, s20, 0x3fffffc0
	s_lshl_b32 s20, s20, 2
	v_and_b32_e32 v219, 31, v2
	s_add_i32 s21, s20, 0
	s_lshl_b32 s20, s24, 5
	v_or_b32_e32 v0, s20, v219
	s_waitcnt lgkmcnt(0)
	v_ashrrev_i32_e32 v1, 31, v0
	v_bfe_u32 v218, v2, 5, 1
	v_lshlrev_b64 v[0:1], 11, v[0:1]
	v_lshl_add_u64 v[0:1], s[22:23], 0, v[0:1]
	v_lshlrev_b32_e32 v210, 4, v218
	v_lshl_add_u64 v[0:1], v[0:1], 0, v[210:211]
	global_load_dwordx4 v[160:163], v[0:1], off
	global_load_dwordx4 v[164:167], v[0:1], off offset:32
	global_load_dwordx4 v[168:171], v[0:1], off offset:64
	global_load_dwordx4 v[172:175], v[0:1], off offset:96
	global_load_dwordx4 v[176:179], v[0:1], off offset:128
	global_load_dwordx4 v[180:183], v[0:1], off offset:160
	global_load_dwordx4 v[184:187], v[0:1], off offset:192
	global_load_dwordx4 v[188:191], v[0:1], off offset:224
	s_lshl_b32 s22, s24, 3
	v_bfe_u32 v1, v2, 4, 2
	v_or_b32_e32 v0, s22, v1
	v_bitop3_b32 v4, v1, v2, 15 bitop3:0x78
	v_ashrrev_i32_e32 v1, 31, v0
	v_lshlrev_b64 v[212:213], 10, v[0:1]
	v_or_b32_e32 v0, 4, v0
	v_and_b32_e32 v3, 15, v2
	v_ashrrev_i32_e32 v1, 31, v0
	v_bitop3_b32 v3, v0, v3, 7 bitop3:0x6c
	v_lshlrev_b64 v[214:215], 10, v[0:1]
	v_bfe_u32 v0, v2, 2, 3
	v_bitop3_b32 v0, s22, -13, v0 bitop3:0xc8
	v_lshrrev_b32_e32 v1, 1, v2
	s_lshl_b32 s22, s24, 2
	v_and_b32_e32 v1, 8, v1
	s_and_b32 s22, s22, 4
	v_or3_b32 v0, v0, v1, s22
	s_add_i32 s21, s21, 0x24000
	v_ashrrev_i32_e32 v1, 31, v0
	v_lshlrev_b32_e32 v11, 3, v2
	s_lshl_b32 s22, s24, 11
	v_lshl_or_b32 v212, v4, 3, v212
	v_lshlrev_b64 v[216:217], 10, v[0:1]
	v_and_b32_e32 v0, 32, v2
	v_and_b32_e32 v1, 24, v11
	s_cmp_lg_u32 0, -1
	v_or3_b32 v216, v216, v1, v0
	v_lshlrev_b64 v[0:1], 1, v[212:213]
	s_cselect_b32 s23, 0, 0
	v_and_b32_e32 v10, 63, v2
	v_lshl_or_b32 v214, v3, 3, v214
	v_lshlrev_b32_e32 v12, 4, v2
	v_lshlrev_b32_e32 v13, 1, v2
	v_lshl_add_u64 v[2:3], s[0:1], 0, v[0:1]
	s_add_i32 s75, s22, s23
	s_mov_b32 s25, m0
	s_mov_b32 m0, s75
	s_nop 0
	global_load_lds_dwordx4 v[2:3], off
	s_mov_b32 m0, s25
	v_lshlrev_b64 v[2:3], 1, v[214:215]
	s_or_b32 s25, s22, 0x400
	v_lshl_add_u64 v[4:5], s[0:1], 0, v[2:3]
	s_add_i32 s77, s25, s23
	s_mov_b32 s84, m0
	s_mov_b32 m0, s77
	s_nop 0
	global_load_lds_dwordx4 v[4:5], off
	s_mov_b32 m0, s84
	s_lshl_b32 s24, s24, 12
	v_lshlrev_b64 v[4:5], 1, v[216:217]
	s_add_i32 s84, s23, 0xc000
	v_lshl_add_u64 v[6:7], s[14:15], 0, v[4:5]
	s_add_i32 s77, s24, s84
	s_mov_b32 s85, m0
	s_mov_b32 m0, s77
	s_nop 0
	global_load_lds_dwordx4 v[6:7], off
	s_mov_b32 m0, s85
	s_or_b32 s85, s24, 0x400
	s_add_i32 s86, s85, s84
	v_lshl_add_u64 v[8:9], v[6:7], 0, s[8:9]
	s_mov_b32 s87, m0
	s_mov_b32 m0, s86
	s_nop 0
	global_load_lds_dwordx4 v[8:9], off
	s_mov_b32 m0, s87
	s_or_b32 s86, s24, 0x800
	s_add_i32 s87, s86, s84
	v_lshl_add_u64 v[8:9], v[6:7], 0, s[10:11]
	s_mov_b32 s96, m0
	s_mov_b32 m0, s87
	s_nop 0
	global_load_lds_dwordx4 v[8:9], off
	s_mov_b32 m0, s96
	s_or_b32 s87, s24, 0xc00
	s_add_i32 s96, s87, s84
	s_add_u32 s0, s0, 0x20000
	v_lshl_add_u64 v[6:7], v[6:7], 0, s[12:13]
	s_mov_b32 s97, m0
	s_mov_b32 m0, s96
	s_nop 0
	global_load_lds_dwordx4 v[6:7], off
	s_mov_b32 m0, s97
	s_addc_u32 s1, s1, 0
	s_add_i32 s96, s23, 0x4000
	v_lshl_add_u64 v[0:1], s[0:1], 0, v[0:1]
	s_add_i32 s22, s22, s96
	s_mov_b32 s97, m0
	s_mov_b32 m0, s22
	s_nop 0
	global_load_lds_dwordx4 v[0:1], off
	s_mov_b32 m0, s97
	v_lshl_add_u64 v[0:1], s[0:1], 0, v[2:3]
	s_add_i32 s25, s25, s96
	s_mov_b32 s0, m0
	s_mov_b32 m0, s25
	s_nop 0
	global_load_lds_dwordx4 v[0:1], off
	s_mov_b32 m0, s0
	s_add_i32 s23, s23, 0x14000
	v_lshl_add_u64 v[0:1], s[16:17], 0, v[4:5]
	s_add_i32 s24, s24, s23
	s_mov_b32 s0, m0
	s_mov_b32 m0, s24
	s_nop 0
	global_load_lds_dwordx4 v[0:1], off
	s_mov_b32 m0, s0
	v_lshl_add_u64 v[2:3], v[0:1], 0, s[8:9]
	s_add_i32 s85, s85, s23
	s_mov_b32 s0, m0
	s_mov_b32 m0, s85
	s_nop 0
	global_load_lds_dwordx4 v[2:3], off
	s_mov_b32 m0, s0
	v_lshl_add_u64 v[2:3], v[0:1], 0, s[10:11]
	s_add_i32 s86, s86, s23
	s_mov_b32 s0, m0
	s_mov_b32 m0, s86
	s_nop 0
	global_load_lds_dwordx4 v[2:3], off
	s_mov_b32 m0, s0
	v_lshl_add_u64 v[0:1], v[0:1], 0, s[12:13]
	s_add_i32 s87, s87, s23
	s_mov_b32 s0, m0
	s_mov_b32 m0, s87
	s_nop 0
	global_load_lds_dwordx4 v[0:1], off
	s_mov_b32 m0, s0
	s_movk_i32 s0, 0x70
	v_and_b32_e32 v1, 0x70, v12
	v_bitop3_b32 v221, v210, v12, s0 bitop3:0x78
	s_movk_i32 s0, 0x60
	v_bitop3_b32 v224, v210, v1, s0 bitop3:0x36
	s_movk_i32 s0, 0x80
	v_and_b32_e32 v0, 0x118, v11
	v_bitop3_b32 v225, v210, v1, s0 bitop3:0x36
	s_movk_i32 s0, 0xa0
	v_and_b32_e32 v14, 0xc0, v12
	v_bitop3_b32 v227, v210, v1, s0 bitop3:0x36
	s_movk_i32 s0, 0xc0
	v_and_or_b32 v0, v13, 32, v0
	v_bitop3_b32 v228, v210, v1, s0 bitop3:0x36
	s_movk_i32 s0, 0xe0
	v_add3_u32 v230, v14, s84, v0
	v_mov_b32_e32 v14, v211
	v_mov_b32_e32 v15, v211
	v_bitop3_b32 v222, v210, v1, 32 bitop3:0x36
	v_bitop3_b32 v223, v210, v1, 64 bitop3:0x36
	v_bitop3_b32 v229, v210, v1, s0 bitop3:0x36
	v_cmp_gt_u32_e64 s[0:1], 32, v10
	s_add_u32 s84, s66, s4
	v_mov_b32_e32 v0, v211
	v_mov_b32_e32 v1, v211
	v_mov_b32_e32 v2, v211
	v_mov_b32_e32 v3, v211
	v_mov_b32_e32 v4, v211
	v_mov_b32_e32 v5, v211
	v_mov_b32_e32 v6, v211
	v_mov_b32_e32 v7, v211
	v_mov_b32_e32 v8, v211
	v_mov_b32_e32 v9, v211
	v_mov_b32_e32 v10, v211
	v_mov_b32_e32 v11, v211
	v_mov_b32_e32 v12, v211
	v_mov_b32_e32 v13, v211
	v_mov_b64_e32 v[126:127], v[14:15]
	v_mov_b64_e32 v[110:111], v[14:15]
	v_mov_b64_e32 v[94:95], v[14:15]
	v_mov_b64_e32 v[78:79], v[14:15]
	v_mov_b64_e32 v[62:63], v[14:15]
	v_mov_b64_e32 v[46:47], v[14:15]
	v_mov_b64_e32 v[30:31], v[14:15]
	s_mov_b32 s74, 2
	s_mov_b32 s76, 0
	v_lshlrev_b32_e32 v220, 8, v219
	v_lshl_add_u32 v226, v219, 2, s21
	s_addc_u32 s85, s67, s5
	v_mov_b32_e32 v232, 0
	v_mov_b32_e32 v231, 0xf149f2ca
	v_mul_f32_e32 v236, 0xbe0293ee, v231
	s_mov_b64 s[22:23], 0
	v_mov_b64_e32 v[124:125], v[12:13]
	v_mov_b64_e32 v[122:123], v[10:11]
	v_mov_b64_e32 v[120:121], v[8:9]
	v_mov_b64_e32 v[118:119], v[6:7]
	v_mov_b64_e32 v[116:117], v[4:5]
	v_mov_b64_e32 v[114:115], v[2:3]
	v_mov_b64_e32 v[112:113], v[0:1]
	v_mov_b64_e32 v[108:109], v[12:13]
	v_mov_b64_e32 v[106:107], v[10:11]
	v_mov_b64_e32 v[104:105], v[8:9]
	v_mov_b64_e32 v[102:103], v[6:7]
	v_mov_b64_e32 v[100:101], v[4:5]
	v_mov_b64_e32 v[98:99], v[2:3]
	v_mov_b64_e32 v[96:97], v[0:1]
	v_mov_b64_e32 v[92:93], v[12:13]
	v_mov_b64_e32 v[90:91], v[10:11]
	v_mov_b64_e32 v[88:89], v[8:9]
	v_mov_b64_e32 v[86:87], v[6:7]
	v_mov_b64_e32 v[84:85], v[4:5]
	v_mov_b64_e32 v[82:83], v[2:3]
	v_mov_b64_e32 v[80:81], v[0:1]
	v_mov_b64_e32 v[76:77], v[12:13]
	v_mov_b64_e32 v[74:75], v[10:11]
	v_mov_b64_e32 v[72:73], v[8:9]
	v_mov_b64_e32 v[70:71], v[6:7]
	v_mov_b64_e32 v[68:69], v[4:5]
	v_mov_b64_e32 v[66:67], v[2:3]
	v_mov_b64_e32 v[64:65], v[0:1]
	v_mov_b64_e32 v[60:61], v[12:13]
	v_mov_b64_e32 v[58:59], v[10:11]
	v_mov_b64_e32 v[56:57], v[8:9]
	v_mov_b64_e32 v[54:55], v[6:7]
	v_mov_b64_e32 v[52:53], v[4:5]
	v_mov_b64_e32 v[50:51], v[2:3]
	v_mov_b64_e32 v[48:49], v[0:1]
	v_mov_b64_e32 v[44:45], v[12:13]
	v_mov_b64_e32 v[42:43], v[10:11]
	v_mov_b64_e32 v[40:41], v[8:9]
	v_mov_b64_e32 v[38:39], v[6:7]
	v_mov_b64_e32 v[36:37], v[4:5]
	v_mov_b64_e32 v[34:35], v[2:3]
	v_mov_b64_e32 v[32:33], v[0:1]
	v_mov_b64_e32 v[28:29], v[12:13]
	v_mov_b64_e32 v[26:27], v[10:11]
	v_mov_b64_e32 v[24:25], v[8:9]
	v_mov_b64_e32 v[22:23], v[6:7]
	v_mov_b64_e32 v[20:21], v[4:5]
	v_mov_b64_e32 v[18:19], v[2:3]
	v_mov_b64_e32 v[16:17], v[0:1]
	s_mov_b32 s86, 0
	s_cmp_eq_u32 s22, 0x7e0000
	s_mov_b64 s[4:5], -1
	s_cbranch_scc0 .LBB0_519

.LBB0_513:
	s_lshl_b32 s4, s76, 14
	s_add_i32 s4, s4, 0
	v_add3_u32 v132, s4, v221, v220
	ds_read_b128 v[128:131], v132
	ds_read_b128 v[132:135], v132 offset:8192
	v_add3_u32 v196, s4, v222, v220
	ds_read_b128 v[192:195], v196
	ds_read_b128 v[196:199], v196 offset:8192
	s_waitcnt lgkmcnt(3)
	v_mfma_f32_32x32x16_bf16 v[144:159], v[128:131], v[160:163], 0
	s_waitcnt lgkmcnt(2)
	v_mfma_f32_32x32x16_bf16 v[128:143], v[132:135], v[160:163], 0
	s_waitcnt lgkmcnt(1)
	v_mfma_f32_32x32x16_bf16 v[144:159], v[192:195], v[164:167], v[144:159]
	s_waitcnt lgkmcnt(0)
	v_mfma_f32_32x32x16_bf16 v[128:143], v[196:199], v[164:167], v[128:143]
	v_add3_u32 v196, s4, v223, v220
	ds_read_b128 v[192:195], v196
	ds_read_b128 v[196:199], v196 offset:8192
	s_waitcnt lgkmcnt(1)
	v_mfma_f32_32x32x16_bf16 v[144:159], v[192:195], v[168:171], v[144:159]
	s_waitcnt lgkmcnt(0)
	v_mfma_f32_32x32x16_bf16 v[128:143], v[196:199], v[168:171], v[128:143]
	v_add3_u32 v196, s4, v224, v220
	ds_read_b128 v[192:195], v196
	ds_read_b128 v[196:199], v196 offset:8192
	s_waitcnt lgkmcnt(1)
	v_mfma_f32_32x32x16_bf16 v[144:159], v[192:195], v[172:175], v[144:159]
	s_waitcnt lgkmcnt(0)
	v_mfma_f32_32x32x16_bf16 v[128:143], v[196:199], v[172:175], v[128:143]
	v_add3_u32 v196, s4, v225, v220
	ds_read_b128 v[192:195], v196
	ds_read_b128 v[196:199], v196 offset:8192
	s_waitcnt lgkmcnt(1)
	v_mfma_f32_32x32x16_bf16 v[144:159], v[192:195], v[176:179], v[144:159]
	s_waitcnt lgkmcnt(0)
	v_mfma_f32_32x32x16_bf16 v[128:143], v[196:199], v[176:179], v[128:143]
	v_add3_u32 v196, s4, v227, v220
	ds_read_b128 v[192:195], v196
	ds_read_b128 v[196:199], v196 offset:8192
	s_waitcnt lgkmcnt(1)
	v_mfma_f32_32x32x16_bf16 v[144:159], v[192:195], v[180:183], v[144:159]
	s_waitcnt lgkmcnt(0)
	v_mfma_f32_32x32x16_bf16 v[128:143], v[196:199], v[180:183], v[128:143]
	v_add3_u32 v196, s4, v228, v220
	ds_read_b128 v[192:195], v196
	ds_read_b128 v[196:199], v196 offset:8192
	s_waitcnt lgkmcnt(1)
	v_mfma_f32_32x32x16_bf16 v[144:159], v[192:195], v[184:187], v[144:159]
	s_waitcnt lgkmcnt(0)
	v_mfma_f32_32x32x16_bf16 v[128:143], v[196:199], v[184:187], v[128:143]
	v_add3_u32 v196, s4, v229, v220
	ds_read_b128 v[192:195], v196
	ds_read_b128 v[196:199], v196 offset:8192
	s_waitcnt lgkmcnt(1)
	v_mfma_f32_32x32x16_bf16 v[144:159], v[192:195], v[188:191], v[144:159]
	s_waitcnt lgkmcnt(0)
	v_mfma_f32_32x32x16_bf16 v[128:143], v[196:199], v[188:191], v[128:143]
	s_nop 9
	v_max_f32_e32 v192, v144, v145
	v_max3_f32 v192, v192, v146, v147
	v_max3_f32 v192, v192, v148, v149
	v_max3_f32 v192, v192, v150, v151
	v_max3_f32 v192, v192, v152, v153
	v_max3_f32 v192, v192, v154, v155
	v_max3_f32 v192, v192, v156, v157
	v_max3_f32 v192, v192, v158, v159
	v_max3_f32 v192, v192, v128, v129
	v_max3_f32 v192, v192, v130, v131
	v_max3_f32 v192, v192, v132, v133
	v_max3_f32 v192, v192, v134, v135
	v_max3_f32 v192, v192, v136, v137
	v_max3_f32 v192, v192, v138, v139
	v_max3_f32 v192, v192, v140, v141
	v_max3_f32 v192, v192, v142, v143
	v_mov_b32_e32 v193, v192
	s_nop 1
	v_permlane32_swap_b32_e32 v192, v193
	v_max_f32_e32 v192, v192, v193
	v_sub_f32_e32 v193, v192, v231
	v_cmp_ge_f32_e32 vcc, s38, v193
	s_cmp_eq_u64 vcc, exec
	s_cbranch_scc0 .Lsmf1_slow
	v_mov_b32_e32 v233, 1.0
	s_branch .Lsmf1_join
.Lsmf1_slow:
	v_max_f32_e32 v234, v231, v192
	v_sub_f32_e32 v192, v231, v234
	v_mul_f32_e32 v192, 0x3e0293ee, v192
	v_exp_f32_e32 v192, v192
	s_cselect_b64 s[4:5], -1, 0
	v_cndmask_b32_e64 v233, v192, 1.0, s[4:5]
	v_cmp_gt_f32_e32 vcc, 1.0, v233
	s_cbranch_vccz .LBB0_517
	s_and_saveexec_b64 s[24:25], s[0:1]
	ds_write_b32 v226, v233 offset:128
	s_or_b64 exec, exec, s[24:25]
	s_waitcnt lgkmcnt(0)
	v_add_u32_e32 v192, s21, v210
	ds_read_b128 v[204:207], v192 offset:224
	ds_read_b128 v[200:203], v192 offset:192
	ds_read_b128 v[196:199], v192 offset:160
	ds_read_b128 v[192:195], v192 offset:128
	s_waitcnt lgkmcnt(3)
	v_pk_mul_f32 v[12:13], v[12:13], v[204:205]
	s_waitcnt lgkmcnt(2)
	v_pk_mul_f32 v[8:9], v[8:9], v[200:201]
	s_waitcnt lgkmcnt(1)
	v_pk_mul_f32 v[4:5], v[4:5], v[196:197]
	v_pk_mul_f32 v[14:15], v[14:15], v[206:207]
	v_pk_mul_f32 v[10:11], v[10:11], v[202:203]
	v_pk_mul_f32 v[6:7], v[6:7], v[198:199]
	s_waitcnt lgkmcnt(0)
	v_pk_mul_f32 v[2:3], v[2:3], v[194:195]
	v_pk_mul_f32 v[0:1], v[0:1], v[192:193]
	v_pk_mul_f32 v[124:125], v[124:125], v[204:205]
	v_pk_mul_f32 v[120:121], v[120:121], v[200:201]
	v_pk_mul_f32 v[116:117], v[116:117], v[196:197]
	v_pk_mul_f32 v[126:127], v[126:127], v[206:207]
	v_pk_mul_f32 v[122:123], v[122:123], v[202:203]
	v_pk_mul_f32 v[118:119], v[118:119], v[198:199]
	v_pk_mul_f32 v[114:115], v[114:115], v[194:195]
	v_pk_mul_f32 v[112:113], v[112:113], v[192:193]
	v_pk_mul_f32 v[108:109], v[108:109], v[204:205]
	v_pk_mul_f32 v[104:105], v[104:105], v[200:201]
	v_pk_mul_f32 v[100:101], v[100:101], v[196:197]
	v_pk_mul_f32 v[110:111], v[110:111], v[206:207]
	v_pk_mul_f32 v[106:107], v[106:107], v[202:203]
	v_pk_mul_f32 v[102:103], v[102:103], v[198:199]
	v_pk_mul_f32 v[98:99], v[98:99], v[194:195]
	v_pk_mul_f32 v[96:97], v[96:97], v[192:193]
	v_pk_mul_f32 v[92:93], v[92:93], v[204:205]
	v_pk_mul_f32 v[88:89], v[88:89], v[200:201]
	v_pk_mul_f32 v[84:85], v[84:85], v[196:197]
	v_pk_mul_f32 v[94:95], v[94:95], v[206:207]
	v_pk_mul_f32 v[90:91], v[90:91], v[202:203]
	v_pk_mul_f32 v[86:87], v[86:87], v[198:199]
	v_pk_mul_f32 v[82:83], v[82:83], v[194:195]
	v_pk_mul_f32 v[80:81], v[80:81], v[192:193]
	v_pk_mul_f32 v[76:77], v[76:77], v[204:205]
	v_pk_mul_f32 v[72:73], v[72:73], v[200:201]
	v_pk_mul_f32 v[68:69], v[68:69], v[196:197]
	v_pk_mul_f32 v[78:79], v[78:79], v[206:207]
	v_pk_mul_f32 v[74:75], v[74:75], v[202:203]
	v_pk_mul_f32 v[70:71], v[70:71], v[198:199]
	v_pk_mul_f32 v[66:67], v[66:67], v[194:195]
	v_pk_mul_f32 v[64:65], v[64:65], v[192:193]
	v_pk_mul_f32 v[60:61], v[60:61], v[204:205]
	v_pk_mul_f32 v[56:57], v[56:57], v[200:201]
	v_pk_mul_f32 v[52:53], v[52:53], v[196:197]
	v_pk_mul_f32 v[62:63], v[62:63], v[206:207]
	v_pk_mul_f32 v[58:59], v[58:59], v[202:203]
	v_pk_mul_f32 v[54:55], v[54:55], v[198:199]
	v_pk_mul_f32 v[50:51], v[50:51], v[194:195]
	v_pk_mul_f32 v[48:49], v[48:49], v[192:193]
	v_pk_mul_f32 v[44:45], v[44:45], v[204:205]
	v_pk_mul_f32 v[40:41], v[40:41], v[200:201]
	v_pk_mul_f32 v[36:37], v[36:37], v[196:197]
	v_pk_mul_f32 v[46:47], v[46:47], v[206:207]
	v_pk_mul_f32 v[42:43], v[42:43], v[202:203]
	v_pk_mul_f32 v[38:39], v[38:39], v[198:199]
	v_pk_mul_f32 v[34:35], v[34:35], v[194:195]
	v_pk_mul_f32 v[32:33], v[32:33], v[192:193]
	v_pk_mul_f32 v[28:29], v[28:29], v[204:205]
	v_pk_mul_f32 v[24:25], v[24:25], v[200:201]
	v_pk_mul_f32 v[20:21], v[20:21], v[196:197]
	v_pk_mul_f32 v[30:31], v[30:31], v[206:207]
	v_pk_mul_f32 v[26:27], v[26:27], v[202:203]
	v_pk_mul_f32 v[22:23], v[22:23], v[198:199]
	v_pk_mul_f32 v[18:19], v[18:19], v[194:195]
	v_pk_mul_f32 v[16:17], v[16:17], v[192:193]
.LBB0_517:
	v_cndmask_b32_e64 v231, v234, v231, s[4:5]
	v_mul_f32_e32 v236, 0xbe0293ee, v231
.Lsmf1_join:
	v_fmamk_f32 v144, v144, 0x3e0293ee, v236
	v_fmamk_f32 v145, v145, 0x3e0293ee, v236
	v_fmamk_f32 v146, v146, 0x3e0293ee, v236
	v_fmamk_f32 v147, v147, 0x3e0293ee, v236
	v_fmamk_f32 v148, v148, 0x3e0293ee, v236
	v_fmamk_f32 v149, v149, 0x3e0293ee, v236
	v_fmamk_f32 v150, v150, 0x3e0293ee, v236
	v_fmamk_f32 v151, v151, 0x3e0293ee, v236
	v_fmamk_f32 v152, v152, 0x3e0293ee, v236
	v_fmamk_f32 v153, v153, 0x3e0293ee, v236
	v_fmamk_f32 v154, v154, 0x3e0293ee, v236
	v_fmamk_f32 v155, v155, 0x3e0293ee, v236
	v_fmamk_f32 v156, v156, 0x3e0293ee, v236
	v_fmamk_f32 v157, v157, 0x3e0293ee, v236
	v_fmamk_f32 v158, v158, 0x3e0293ee, v236
	v_fmamk_f32 v159, v159, 0x3e0293ee, v236
	v_fmamk_f32 v128, v128, 0x3e0293ee, v236
	v_fmamk_f32 v129, v129, 0x3e0293ee, v236
	v_fmamk_f32 v130, v130, 0x3e0293ee, v236
	v_fmamk_f32 v131, v131, 0x3e0293ee, v236
	v_fmamk_f32 v132, v132, 0x3e0293ee, v236
	v_fmamk_f32 v133, v133, 0x3e0293ee, v236
	v_fmamk_f32 v134, v134, 0x3e0293ee, v236
	v_fmamk_f32 v135, v135, 0x3e0293ee, v236
	v_fmamk_f32 v136, v136, 0x3e0293ee, v236
	v_fmamk_f32 v137, v137, 0x3e0293ee, v236
	v_fmamk_f32 v138, v138, 0x3e0293ee, v236
	v_fmamk_f32 v139, v139, 0x3e0293ee, v236
	v_fmamk_f32 v140, v140, 0x3e0293ee, v236
	v_fmamk_f32 v141, v141, 0x3e0293ee, v236
	v_fmamk_f32 v142, v142, 0x3e0293ee, v236
	v_fmamk_f32 v192, v143, 0x3e0293ee, v236
	v_exp_f32_e32 v143, v144
	v_exp_f32_e32 v145, v145
	v_exp_f32_e32 v146, v146
	v_exp_f32_e32 v147, v147
	v_exp_f32_e32 v148, v148
	v_exp_f32_e32 v193, v128
	v_exp_f32_e32 v149, v149
	v_add_f32_e32 v128, v145, v143
	v_exp_f32_e32 v150, v150
	v_add_f32_e32 v128, v146, v128
	v_exp_f32_e32 v151, v151
	v_add_f32_e32 v128, v147, v128
	v_exp_f32_e32 v152, v152
	v_add_f32_e32 v128, v148, v128
	v_exp_f32_e32 v153, v153
	v_add_f32_e32 v128, v149, v128
	v_exp_f32_e32 v154, v154
	v_add_f32_e32 v128, v150, v128
	v_exp_f32_e32 v155, v155
	v_add_f32_e32 v128, v151, v128
	v_exp_f32_e32 v156, v156
	v_add_f32_e32 v128, v152, v128
	v_exp_f32_e32 v157, v157
	v_add_f32_e32 v128, v153, v128
	v_exp_f32_e32 v158, v158
	v_add_f32_e32 v128, v154, v128
	v_exp_f32_e32 v159, v159
	v_add_f32_e32 v128, v155, v128
	v_add_f32_e32 v128, v156, v128
	v_exp_f32_e32 v194, v129
	v_add_f32_e32 v128, v157, v128
	v_exp_f32_e32 v195, v130
	v_add_f32_e32 v128, v158, v128
	v_exp_f32_e32 v196, v131
	v_add_f32_e32 v128, v159, v128
	v_exp_f32_e32 v197, v132
	v_add_f32_e32 v128, v193, v128
	v_exp_f32_e32 v198, v133
	v_add_f32_e32 v128, v194, v128
	v_exp_f32_e32 v199, v134
	v_add_f32_e32 v128, v195, v128
	v_exp_f32_e32 v135, v135
	v_add_f32_e32 v128, v196, v128
	v_exp_f32_e32 v200, v136
	v_add_f32_e32 v128, v197, v128
	v_exp_f32_e32 v201, v137
	v_add_f32_e32 v128, v198, v128
	v_exp_f32_e32 v202, v138
	v_add_f32_e32 v128, v199, v128
	v_exp_f32_e32 v203, v139
	v_add_f32_e32 v128, v135, v128
	v_exp_f32_e32 v204, v140
	v_add_f32_e32 v128, v200, v128
	v_exp_f32_e32 v205, v141
	v_add_f32_e32 v128, v201, v128
	v_exp_f32_e32 v206, v142
	v_add_f32_e32 v128, v202, v128
	v_exp_f32_e32 v192, v192
	v_add_f32_e32 v128, v203, v128
	v_add_f32_e32 v128, v204, v128
	v_add_f32_e32 v128, v205, v128
	v_add_f32_e32 v128, v206, v128
	v_add_f32_e32 v128, v192, v128
	v_mov_b32_e32 v129, v128
	s_nop 1
	v_permlane32_swap_b32_e32 v128, v129
	v_add_f32_e32 v144, v128, v129
	v_fmac_f32_e32 v144, v232, v233
	v_cvt_pk_bf16_f32 v128, v143, v145
	v_cvt_pk_bf16_f32 v129, v146, v147
	v_cvt_pk_bf16_f32 v130, v148, v149
	v_cvt_pk_bf16_f32 v131, v150, v151
	v_cvt_pk_bf16_f32 v136, v152, v153
	v_cvt_pk_bf16_f32 v137, v154, v155
	v_cvt_pk_bf16_f32 v138, v156, v157
	v_cvt_pk_bf16_f32 v139, v158, v159
	v_cvt_pk_bf16_f32 v132, v193, v194
	v_cvt_pk_bf16_f32 v133, v195, v196
	v_cvt_pk_bf16_f32 v134, v197, v198
	v_cvt_pk_bf16_f32 v135, v199, v135
	v_cvt_pk_bf16_f32 v140, v200, v201
	v_cvt_pk_bf16_f32 v141, v202, v203
	v_cvt_pk_bf16_f32 v142, v204, v205
	v_cvt_pk_bf16_f32 v143, v206, v192
	s_nop 0
	v_permlane32_swap_b32_e32 v128, v130
	v_permlane32_swap_b32_e32 v129, v131
	v_permlane32_swap_b32_e32 v136, v138
	v_permlane32_swap_b32_e32 v137, v139
	v_permlane32_swap_b32_e32 v132, v134
	v_permlane32_swap_b32_e32 v133, v135
	v_permlane32_swap_b32_e32 v140, v142
	v_permlane32_swap_b32_e32 v141, v143
	v_lshl_add_u32 v145, s76, 15, v230
	ds_read_b64_tr_b16 v[146:147], v145 offset:0
	ds_read_b64_tr_b16 v[148:149], v145 offset:0x1000
	ds_read_b64_tr_b16 v[150:151], v145 offset:0x2000
	ds_read_b64_tr_b16 v[152:153], v145 offset:0x3000
	ds_read_b64_tr_b16 v[154:155], v145 offset:0x4000
	ds_read_b64_tr_b16 v[156:157], v145 offset:0x5000
	ds_read_b64_tr_b16 v[192:193], v145 offset:0x6000
	ds_read_b64_tr_b16 v[194:195], v145 offset:0x7000
	ds_read_b64_tr_b16 v[196:197], v145 offset:0x200
	ds_read_b64_tr_b16 v[198:199], v145 offset:0x1200
	ds_read_b64_tr_b16 v[200:201], v145 offset:0x2200
	ds_read_b64_tr_b16 v[202:203], v145 offset:0x3200
	ds_read_b64_tr_b16 v[204:205], v145 offset:0x4200
	ds_read_b64_tr_b16 v[206:207], v145 offset:0x5200
	ds_read_b64_tr_b16 v[232:233], v145 offset:0x6200
	ds_read_b64_tr_b16 v[234:235], v145 offset:0x7200
	s_waitcnt lgkmcnt(8)
	s_nop 0
	v_mfma_f32_32x32x16_bf16 v[0:15], v[128:131], v[146:149], v[0:15]
	v_mfma_f32_32x32x16_bf16 v[0:15], v[136:139], v[150:153], v[0:15]
	v_mfma_f32_32x32x16_bf16 v[0:15], v[132:135], v[154:157], v[0:15]
	v_mfma_f32_32x32x16_bf16 v[0:15], v[140:143], v[192:195], v[0:15]
	ds_read_b64_tr_b16 v[146:147], v145 offset:0x400
	ds_read_b64_tr_b16 v[148:149], v145 offset:0x1400
	ds_read_b64_tr_b16 v[150:151], v145 offset:0x2400
	ds_read_b64_tr_b16 v[152:153], v145 offset:0x3400
	ds_read_b64_tr_b16 v[154:155], v145 offset:0x4400
	ds_read_b64_tr_b16 v[156:157], v145 offset:0x5400
	ds_read_b64_tr_b16 v[192:193], v145 offset:0x6400
	ds_read_b64_tr_b16 v[194:195], v145 offset:0x7400
	s_waitcnt lgkmcnt(8)
	v_mfma_f32_32x32x16_bf16 v[112:127], v[128:131], v[196:199], v[112:127]
	v_mfma_f32_32x32x16_bf16 v[112:127], v[136:139], v[200:203], v[112:127]
	v_mfma_f32_32x32x16_bf16 v[112:127], v[132:135], v[204:207], v[112:127]
	v_mfma_f32_32x32x16_bf16 v[112:127], v[140:143], v[232:235], v[112:127]
	ds_read_b64_tr_b16 v[196:197], v145 offset:0x600
	ds_read_b64_tr_b16 v[198:199], v145 offset:0x1600
	ds_read_b64_tr_b16 v[200:201], v145 offset:0x2600
	ds_read_b64_tr_b16 v[202:203], v145 offset:0x3600
	ds_read_b64_tr_b16 v[204:205], v145 offset:0x4600
	ds_read_b64_tr_b16 v[206:207], v145 offset:0x5600
	ds_read_b64_tr_b16 v[232:233], v145 offset:0x6600
	ds_read_b64_tr_b16 v[234:235], v145 offset:0x7600
	s_waitcnt lgkmcnt(8)
	v_mfma_f32_32x32x16_bf16 v[96:111], v[128:131], v[146:149], v[96:111]
	v_mfma_f32_32x32x16_bf16 v[96:111], v[136:139], v[150:153], v[96:111]
	v_mfma_f32_32x32x16_bf16 v[96:111], v[132:135], v[154:157], v[96:111]
	v_mfma_f32_32x32x16_bf16 v[96:111], v[140:143], v[192:195], v[96:111]
	ds_read_b64_tr_b16 v[146:147], v145 offset:0x800
	ds_read_b64_tr_b16 v[148:149], v145 offset:0x1800
	ds_read_b64_tr_b16 v[150:151], v145 offset:0x2800
	ds_read_b64_tr_b16 v[152:153], v145 offset:0x3800
	ds_read_b64_tr_b16 v[154:155], v145 offset:0x4800
	ds_read_b64_tr_b16 v[156:157], v145 offset:0x5800
	ds_read_b64_tr_b16 v[192:193], v145 offset:0x6800
	ds_read_b64_tr_b16 v[194:195], v145 offset:0x7800
	s_waitcnt lgkmcnt(8)
	v_mfma_f32_32x32x16_bf16 v[80:95], v[128:131], v[196:199], v[80:95]
	v_mfma_f32_32x32x16_bf16 v[80:95], v[136:139], v[200:203], v[80:95]
	v_mfma_f32_32x32x16_bf16 v[80:95], v[132:135], v[204:207], v[80:95]
	v_mfma_f32_32x32x16_bf16 v[80:95], v[140:143], v[232:235], v[80:95]
	ds_read_b64_tr_b16 v[196:197], v145 offset:0xa00
	ds_read_b64_tr_b16 v[198:199], v145 offset:0x1a00
	ds_read_b64_tr_b16 v[200:201], v145 offset:0x2a00
	ds_read_b64_tr_b16 v[202:203], v145 offset:0x3a00
	ds_read_b64_tr_b16 v[204:205], v145 offset:0x4a00
	ds_read_b64_tr_b16 v[206:207], v145 offset:0x5a00
	ds_read_b64_tr_b16 v[232:233], v145 offset:0x6a00
	ds_read_b64_tr_b16 v[234:235], v145 offset:0x7a00
	s_waitcnt lgkmcnt(8)
	v_mfma_f32_32x32x16_bf16 v[64:79], v[128:131], v[146:149], v[64:79]
	v_mfma_f32_32x32x16_bf16 v[64:79], v[136:139], v[150:153], v[64:79]
	v_mfma_f32_32x32x16_bf16 v[64:79], v[132:135], v[154:157], v[64:79]
	v_mfma_f32_32x32x16_bf16 v[64:79], v[140:143], v[192:195], v[64:79]
	ds_read_b64_tr_b16 v[146:147], v145 offset:0xc00
	ds_read_b64_tr_b16 v[148:149], v145 offset:0x1c00
	ds_read_b64_tr_b16 v[150:151], v145 offset:0x2c00
	ds_read_b64_tr_b16 v[152:153], v145 offset:0x3c00
	ds_read_b64_tr_b16 v[154:155], v145 offset:0x4c00
	ds_read_b64_tr_b16 v[156:157], v145 offset:0x5c00
	ds_read_b64_tr_b16 v[192:193], v145 offset:0x6c00
	ds_read_b64_tr_b16 v[194:195], v145 offset:0x7c00
	s_waitcnt lgkmcnt(8)
	v_mfma_f32_32x32x16_bf16 v[48:63], v[128:131], v[196:199], v[48:63]
	v_mfma_f32_32x32x16_bf16 v[48:63], v[136:139], v[200:203], v[48:63]
	v_mfma_f32_32x32x16_bf16 v[48:63], v[132:135], v[204:207], v[48:63]
	v_mfma_f32_32x32x16_bf16 v[48:63], v[140:143], v[232:235], v[48:63]
	ds_read_b64_tr_b16 v[196:197], v145 offset:0xe00
	ds_read_b64_tr_b16 v[198:199], v145 offset:0x1e00
	ds_read_b64_tr_b16 v[200:201], v145 offset:0x2e00
	ds_read_b64_tr_b16 v[202:203], v145 offset:0x3e00
	ds_read_b64_tr_b16 v[204:205], v145 offset:0x4e00
	ds_read_b64_tr_b16 v[206:207], v145 offset:0x5e00
	ds_read_b64_tr_b16 v[232:233], v145 offset:0x6e00
	ds_read_b64_tr_b16 v[234:235], v145 offset:0x7e00
	s_waitcnt lgkmcnt(8)
	v_mfma_f32_32x32x16_bf16 v[32:47], v[128:131], v[146:149], v[32:47]
	v_mfma_f32_32x32x16_bf16 v[32:47], v[136:139], v[150:153], v[32:47]
	v_mfma_f32_32x32x16_bf16 v[32:47], v[132:135], v[154:157], v[32:47]
	v_mfma_f32_32x32x16_bf16 v[32:47], v[140:143], v[192:195], v[32:47]
	s_waitcnt lgkmcnt(0)
	v_mfma_f32_32x32x16_bf16 v[16:31], v[128:131], v[196:199], v[16:31]
	s_add_i32 s4, s76, 1
	s_cmp_lg_u32 s76, 2
	s_cselect_b32 s76, s4, 0
	s_add_i32 s4, s74, 1
	s_cmp_lg_u32 s74, 2
	s_cselect_b32 s74, s4, 0
	s_add_u32 s22, s22, 0x20000
	v_mfma_f32_32x32x16_bf16 v[16:31], v[136:139], v[200:203], v[16:31]
	s_addc_u32 s23, s23, 0
	s_add_i32 s86, s86, 1
	s_cmp_eq_u32 s22, 0x800000
	v_mfma_f32_32x32x16_bf16 v[16:31], v[132:135], v[204:207], v[16:31]
	v_mfma_f32_32x32x16_bf16 v[16:31], v[140:143], v[232:235], v[16:31]
	s_cbranch_scc1 .LBB0_521
	v_mov_b32_e32 v232, v144
	s_cmp_eq_u32 s22, 0x7e0000
	s_mov_b64 s[4:5], -1
	s_cbranch_scc1 .LBB0_510

.LBB0_902:
	s_xor_b64 s[18:19], s[4:5], -1
	s_lshl_b64 s[4:5], s[0:1], 1
	s_add_u32 s22, s62, s4
	s_addc_u32 s23, s63, s5
	v_mov_b32_e32 v2, v208
	s_add_u32 s0, s64, s4
	s_addc_u32 s1, s65, s5
	v_readfirstlane_b32 s20, v2
	s_ashr_i32 s24, s20, 6
	s_and_b32 s20, s20, 0x3fffffc0
	s_lshl_b32 s20, s20, 2
	v_and_b32_e32 v219, 31, v2
	s_add_i32 s21, s20, 0
	s_lshl_b32 s20, s24, 5
	v_or_b32_e32 v0, s20, v219
	s_waitcnt lgkmcnt(0)
	v_ashrrev_i32_e32 v1, 31, v0
	v_bfe_u32 v218, v2, 5, 1
	v_lshlrev_b64 v[0:1], 11, v[0:1]
	v_lshl_add_u64 v[0:1], s[22:23], 0, v[0:1]
	v_lshlrev_b32_e32 v210, 4, v218
	v_lshl_add_u64 v[0:1], v[0:1], 0, v[210:211]
	global_load_dwordx4 v[160:163], v[0:1], off
	global_load_dwordx4 v[164:167], v[0:1], off offset:32
	global_load_dwordx4 v[168:171], v[0:1], off offset:64
	global_load_dwordx4 v[172:175], v[0:1], off offset:96
	global_load_dwordx4 v[176:179], v[0:1], off offset:128
	global_load_dwordx4 v[180:183], v[0:1], off offset:160
	global_load_dwordx4 v[184:187], v[0:1], off offset:192
	global_load_dwordx4 v[188:191], v[0:1], off offset:224
	s_lshl_b32 s22, s24, 3
	v_bfe_u32 v1, v2, 4, 2
	v_or_b32_e32 v0, s22, v1
	v_bitop3_b32 v4, v1, v2, 15 bitop3:0x78
	v_ashrrev_i32_e32 v1, 31, v0
	v_lshlrev_b64 v[212:213], 10, v[0:1]
	v_or_b32_e32 v0, 4, v0
	v_and_b32_e32 v3, 15, v2
	v_ashrrev_i32_e32 v1, 31, v0
	v_bitop3_b32 v3, v0, v3, 7 bitop3:0x6c
	v_lshlrev_b64 v[214:215], 10, v[0:1]
	v_bfe_u32 v0, v2, 2, 3
	v_bitop3_b32 v0, s22, -13, v0 bitop3:0xc8
	v_lshrrev_b32_e32 v1, 1, v2
	s_lshl_b32 s22, s24, 2
	v_and_b32_e32 v1, 8, v1
	s_and_b32 s22, s22, 4
	v_or3_b32 v0, v0, v1, s22
	s_add_i32 s21, s21, 0x24000
	v_ashrrev_i32_e32 v1, 31, v0
	v_lshlrev_b32_e32 v11, 3, v2
	s_lshl_b32 s22, s24, 11
	v_lshl_or_b32 v212, v4, 3, v212
	v_lshlrev_b64 v[216:217], 10, v[0:1]
	v_and_b32_e32 v0, 32, v2
	v_and_b32_e32 v1, 24, v11
	s_cmp_lg_u32 0, -1
	v_or3_b32 v216, v216, v1, v0
	v_lshlrev_b64 v[0:1], 1, v[212:213]
	s_cselect_b32 s23, 0, 0
	v_and_b32_e32 v10, 63, v2
	v_lshl_or_b32 v214, v3, 3, v214
	v_lshlrev_b32_e32 v12, 4, v2
	v_lshlrev_b32_e32 v13, 1, v2
	v_lshl_add_u64 v[2:3], s[0:1], 0, v[0:1]
	s_add_i32 s79, s22, s23
	s_mov_b32 s25, m0
	s_mov_b32 m0, s79
	s_nop 0
	global_load_lds_dwordx4 v[2:3], off
	s_mov_b32 m0, s25
	v_lshlrev_b64 v[2:3], 1, v[214:215]
	s_or_b32 s25, s22, 0x400
	v_lshl_add_u64 v[4:5], s[0:1], 0, v[2:3]
	s_add_i32 s81, s25, s23
	s_mov_b32 s84, m0
	s_mov_b32 m0, s81
	s_nop 0
	global_load_lds_dwordx4 v[4:5], off
	s_mov_b32 m0, s84
	s_lshl_b32 s24, s24, 12
	v_lshlrev_b64 v[4:5], 1, v[216:217]
	s_add_i32 s84, s23, 0xc000
	v_lshl_add_u64 v[6:7], s[14:15], 0, v[4:5]
	s_add_i32 s81, s24, s84
	s_mov_b32 s85, m0
	s_mov_b32 m0, s81
	s_nop 0
	global_load_lds_dwordx4 v[6:7], off
	s_mov_b32 m0, s85
	s_or_b32 s85, s24, 0x400
	s_add_i32 s86, s85, s84
	v_lshl_add_u64 v[8:9], v[6:7], 0, s[8:9]
	s_mov_b32 s87, m0
	s_mov_b32 m0, s86
	s_nop 0
	global_load_lds_dwordx4 v[8:9], off
	s_mov_b32 m0, s87
	s_or_b32 s86, s24, 0x800
	s_add_i32 s87, s86, s84
	v_lshl_add_u64 v[8:9], v[6:7], 0, s[10:11]
	s_mov_b32 s96, m0
	s_mov_b32 m0, s87
	s_nop 0
	global_load_lds_dwordx4 v[8:9], off
	s_mov_b32 m0, s96
	s_or_b32 s87, s24, 0xc00
	s_add_i32 s96, s87, s84
	s_add_u32 s0, s0, 0x20000
	v_lshl_add_u64 v[6:7], v[6:7], 0, s[12:13]
	s_mov_b32 s97, m0
	s_mov_b32 m0, s96
	s_nop 0
	global_load_lds_dwordx4 v[6:7], off
	s_mov_b32 m0, s97
	s_addc_u32 s1, s1, 0
	s_add_i32 s96, s23, 0x4000
	v_lshl_add_u64 v[0:1], s[0:1], 0, v[0:1]
	s_add_i32 s22, s22, s96
	s_mov_b32 s97, m0
	s_mov_b32 m0, s22
	s_nop 0
	global_load_lds_dwordx4 v[0:1], off
	s_mov_b32 m0, s97
	v_lshl_add_u64 v[0:1], s[0:1], 0, v[2:3]
	s_add_i32 s25, s25, s96
	s_mov_b32 s0, m0
	s_mov_b32 m0, s25
	s_nop 0
	global_load_lds_dwordx4 v[0:1], off
	s_mov_b32 m0, s0
	s_add_i32 s23, s23, 0x14000
	v_lshl_add_u64 v[0:1], s[16:17], 0, v[4:5]
	s_add_i32 s24, s24, s23
	s_mov_b32 s0, m0
	s_mov_b32 m0, s24
	s_nop 0
	global_load_lds_dwordx4 v[0:1], off
	s_mov_b32 m0, s0
	v_lshl_add_u64 v[2:3], v[0:1], 0, s[8:9]
	s_add_i32 s85, s85, s23
	s_mov_b32 s0, m0
	s_mov_b32 m0, s85
	s_nop 0
	global_load_lds_dwordx4 v[2:3], off
	s_mov_b32 m0, s0
	v_lshl_add_u64 v[2:3], v[0:1], 0, s[10:11]
	s_add_i32 s86, s86, s23
	s_mov_b32 s0, m0
	s_mov_b32 m0, s86
	s_nop 0
	global_load_lds_dwordx4 v[2:3], off
	s_mov_b32 m0, s0
	v_lshl_add_u64 v[0:1], v[0:1], 0, s[12:13]
	s_add_i32 s87, s87, s23
	s_mov_b32 s0, m0
	s_mov_b32 m0, s87
	s_nop 0
	global_load_lds_dwordx4 v[0:1], off
	s_mov_b32 m0, s0
	v_and_b32_e32 v0, 0x118, v11
	v_and_b32_e32 v14, 0xc0, v12
	s_movk_i32 s0, 0x70
	v_and_or_b32 v0, v13, 32, v0
	v_and_b32_e32 v1, 0x70, v12
	v_bitop3_b32 v221, v210, v12, s0 bitop3:0x78
	s_movk_i32 s0, 0xc0
	v_add3_u32 v230, v14, s84, v0
	v_mov_b32_e32 v14, v211
	v_mov_b32_e32 v15, v211
	v_bitop3_b32 v222, v210, v1, 32 bitop3:0x36
	v_bitop3_b32 v223, v210, v1, 64 bitop3:0x36
	v_bitop3_b32 v225, v210, v1, s38 bitop3:0x36
	v_bitop3_b32 v226, v210, v1, s39 bitop3:0x36
	v_bitop3_b32 v227, v210, v1, s40 bitop3:0x36
	v_bitop3_b32 v228, v210, v1, s0 bitop3:0x36
	v_bitop3_b32 v229, v210, v1, s41 bitop3:0x36
	v_cmp_gt_u32_e64 s[0:1], 32, v10
	s_add_u32 s84, s74, s4
	v_mov_b32_e32 v0, v211
	v_mov_b32_e32 v1, v211
	v_mov_b32_e32 v2, v211
	v_mov_b32_e32 v3, v211
	v_mov_b32_e32 v4, v211
	v_mov_b32_e32 v5, v211
	v_mov_b32_e32 v6, v211
	v_mov_b32_e32 v7, v211
	v_mov_b32_e32 v8, v211
	v_mov_b32_e32 v9, v211
	v_mov_b32_e32 v10, v211
	v_mov_b32_e32 v11, v211
	v_mov_b32_e32 v12, v211
	v_mov_b32_e32 v13, v211
	v_mov_b64_e32 v[126:127], v[14:15]
	v_mov_b64_e32 v[110:111], v[14:15]
	v_mov_b64_e32 v[94:95], v[14:15]
	v_mov_b64_e32 v[78:79], v[14:15]
	v_mov_b64_e32 v[62:63], v[14:15]
	v_mov_b64_e32 v[46:47], v[14:15]
	v_mov_b64_e32 v[30:31], v[14:15]
	s_mov_b32 s78, 2
	s_mov_b32 s80, 0
	v_lshlrev_b32_e32 v220, 8, v219
	v_lshl_add_u32 v224, v219, 2, s21
	s_addc_u32 s85, s75, s5
	v_mov_b32_e32 v232, 0
	v_mov_b32_e32 v231, 0xf149f2ca
	v_mul_f32_e32 v236, 0xbe0293ee, v231
	s_mov_b64 s[22:23], 0
	v_mov_b64_e32 v[124:125], v[12:13]
	v_mov_b64_e32 v[122:123], v[10:11]
	v_mov_b64_e32 v[120:121], v[8:9]
	v_mov_b64_e32 v[118:119], v[6:7]
	v_mov_b64_e32 v[116:117], v[4:5]
	v_mov_b64_e32 v[114:115], v[2:3]
	v_mov_b64_e32 v[112:113], v[0:1]
	v_mov_b64_e32 v[108:109], v[12:13]
	v_mov_b64_e32 v[106:107], v[10:11]
	v_mov_b64_e32 v[104:105], v[8:9]
	v_mov_b64_e32 v[102:103], v[6:7]
	v_mov_b64_e32 v[100:101], v[4:5]
	v_mov_b64_e32 v[98:99], v[2:3]
	v_mov_b64_e32 v[96:97], v[0:1]
	v_mov_b64_e32 v[92:93], v[12:13]
	v_mov_b64_e32 v[90:91], v[10:11]
	v_mov_b64_e32 v[88:89], v[8:9]
	v_mov_b64_e32 v[86:87], v[6:7]
	v_mov_b64_e32 v[84:85], v[4:5]
	v_mov_b64_e32 v[82:83], v[2:3]
	v_mov_b64_e32 v[80:81], v[0:1]
	v_mov_b64_e32 v[76:77], v[12:13]
	v_mov_b64_e32 v[74:75], v[10:11]
	v_mov_b64_e32 v[72:73], v[8:9]
	v_mov_b64_e32 v[70:71], v[6:7]
	v_mov_b64_e32 v[68:69], v[4:5]
	v_mov_b64_e32 v[66:67], v[2:3]
	v_mov_b64_e32 v[64:65], v[0:1]
	v_mov_b64_e32 v[60:61], v[12:13]
	v_mov_b64_e32 v[58:59], v[10:11]
	v_mov_b64_e32 v[56:57], v[8:9]
	v_mov_b64_e32 v[54:55], v[6:7]
	v_mov_b64_e32 v[52:53], v[4:5]
	v_mov_b64_e32 v[50:51], v[2:3]
	v_mov_b64_e32 v[48:49], v[0:1]
	v_mov_b64_e32 v[44:45], v[12:13]
	v_mov_b64_e32 v[42:43], v[10:11]
	v_mov_b64_e32 v[40:41], v[8:9]
	v_mov_b64_e32 v[38:39], v[6:7]
	v_mov_b64_e32 v[36:37], v[4:5]
	v_mov_b64_e32 v[34:35], v[2:3]
	v_mov_b64_e32 v[32:33], v[0:1]
	v_mov_b64_e32 v[28:29], v[12:13]
	v_mov_b64_e32 v[26:27], v[10:11]
	v_mov_b64_e32 v[24:25], v[8:9]
	v_mov_b64_e32 v[22:23], v[6:7]
	v_mov_b64_e32 v[20:21], v[4:5]
	v_mov_b64_e32 v[18:19], v[2:3]
	v_mov_b64_e32 v[16:17], v[0:1]
	s_mov_b32 s86, 0
	s_cmp_eq_u32 s22, 0x7e0000
	s_mov_b64 s[4:5], -1
	s_cbranch_scc0 .LBB0_912

.LBB0_906:
	s_lshl_b32 s4, s80, 14
	s_add_i32 s4, s4, 0
	v_add3_u32 v132, s4, v221, v220
	ds_read_b128 v[128:131], v132
	ds_read_b128 v[132:135], v132 offset:8192
	v_add3_u32 v196, s4, v222, v220
	ds_read_b128 v[192:195], v196
	ds_read_b128 v[196:199], v196 offset:8192
	v_add3_u32 v200, s4, v227, v220
	s_waitcnt lgkmcnt(3)
	v_mfma_f32_32x32x16_bf16 v[144:159], v[128:131], v[160:163], 0
	s_waitcnt lgkmcnt(2)
	v_mfma_f32_32x32x16_bf16 v[128:143], v[132:135], v[160:163], 0
	s_waitcnt lgkmcnt(1)
	v_mfma_f32_32x32x16_bf16 v[144:159], v[192:195], v[164:167], v[144:159]
	s_waitcnt lgkmcnt(0)
	v_mfma_f32_32x32x16_bf16 v[128:143], v[196:199], v[164:167], v[128:143]
	v_add3_u32 v196, s4, v223, v220
	ds_read_b128 v[192:195], v196
	ds_read_b128 v[196:199], v196 offset:8192
	s_waitcnt lgkmcnt(1)
	v_mfma_f32_32x32x16_bf16 v[144:159], v[192:195], v[168:171], v[144:159]
	s_waitcnt lgkmcnt(0)
	v_mfma_f32_32x32x16_bf16 v[128:143], v[196:199], v[168:171], v[128:143]
	v_add3_u32 v196, s4, v225, v220
	ds_read_b128 v[192:195], v196
	ds_read_b128 v[196:199], v196 offset:8192
	s_waitcnt lgkmcnt(1)
	v_mfma_f32_32x32x16_bf16 v[144:159], v[192:195], v[172:175], v[144:159]
	s_waitcnt lgkmcnt(0)
	v_mfma_f32_32x32x16_bf16 v[128:143], v[196:199], v[172:175], v[128:143]
	v_add3_u32 v196, s4, v226, v220
	ds_read_b128 v[192:195], v196
	ds_read_b128 v[196:199], v196 offset:8192
	s_waitcnt lgkmcnt(1)
	v_mfma_f32_32x32x16_bf16 v[144:159], v[192:195], v[176:179], v[144:159]
	s_waitcnt lgkmcnt(0)
	v_mfma_f32_32x32x16_bf16 v[128:143], v[196:199], v[176:179], v[128:143]
	ds_read_b128 v[192:195], v200
	ds_read_b128 v[196:199], v200 offset:8192
	v_add3_u32 v200, s4, v228, v220
	s_waitcnt lgkmcnt(1)
	v_mfma_f32_32x32x16_bf16 v[144:159], v[192:195], v[180:183], v[144:159]
	s_waitcnt lgkmcnt(0)
	v_mfma_f32_32x32x16_bf16 v[128:143], v[196:199], v[180:183], v[128:143]
	ds_read_b128 v[192:195], v200
	ds_read_b128 v[196:199], v200 offset:8192
	v_add3_u32 v200, s4, v229, v220
	s_waitcnt lgkmcnt(1)
	v_mfma_f32_32x32x16_bf16 v[144:159], v[192:195], v[184:187], v[144:159]
	ds_read_b128 v[192:195], v200
	ds_read_b128 v[200:203], v200 offset:8192
	s_waitcnt lgkmcnt(1)
	v_mfma_f32_32x32x16_bf16 v[144:159], v[192:195], v[188:191], v[144:159]
	v_max_f32_e32 v194, v231, v231
	v_mfma_f32_32x32x16_bf16 v[128:143], v[196:199], v[184:187], v[128:143]
	s_nop 9
	v_max_f32_e32 v192, v144, v145
	v_max3_f32 v192, v192, v146, v147
	v_max3_f32 v192, v192, v148, v149
	v_max3_f32 v192, v192, v150, v151
	v_max3_f32 v192, v192, v152, v153
	s_waitcnt lgkmcnt(0)
	v_mfma_f32_32x32x16_bf16 v[128:143], v[200:203], v[188:191], v[128:143]
	v_max3_f32 v192, v192, v154, v155
	v_max3_f32 v192, v192, v156, v157
	v_max3_f32 v192, v192, v158, v159
	s_nop 8
	v_max3_f32 v192, v192, v128, v129
	v_max3_f32 v192, v192, v130, v131
	v_max3_f32 v192, v192, v132, v133
	v_max3_f32 v192, v192, v134, v135
	v_max3_f32 v192, v192, v136, v137
	v_max3_f32 v192, v192, v138, v139
	v_max3_f32 v192, v192, v140, v141
	v_max3_f32 v192, v192, v142, v143
	v_mov_b32_e32 v193, v192
	s_nop 1
	v_permlane32_swap_b32_e32 v192, v193
	v_max_f32_e32 v192, v192, v193
	v_max_f32_e32 v234, v194, v192
	v_sub_f32_e32 v193, v192, v231
	v_cmp_ge_f32_e32 vcc, s42, v193
	s_cmp_eq_u64 vcc, exec
	s_cbranch_scc0 .Lsmf0_slow
	v_mov_b32_e32 v233, 1.0
	s_branch .Lsmf0_join
.Lsmf0_slow:
	v_sub_f32_e32 v192, v231, v234
	v_mul_f32_e32 v192, 0x3e0293ee, v192
	v_exp_f32_e32 v192, v192
	s_cselect_b64 s[4:5], -1, 0
	v_cndmask_b32_e64 v233, v192, 1.0, s[4:5]
	v_cmp_gt_f32_e32 vcc, 1.0, v233
	s_cbranch_vccz .LBB0_910
	s_and_saveexec_b64 s[24:25], s[0:1]
	ds_write_b32 v224, v233 offset:128
	s_or_b64 exec, exec, s[24:25]
	s_waitcnt lgkmcnt(0)
	v_add_u32_e32 v192, s21, v210
	ds_read_b128 v[204:207], v192 offset:224
	ds_read_b128 v[200:203], v192 offset:192
	ds_read_b128 v[196:199], v192 offset:160
	ds_read_b128 v[192:195], v192 offset:128
	s_waitcnt lgkmcnt(3)
	v_pk_mul_f32 v[12:13], v[12:13], v[204:205]
	s_waitcnt lgkmcnt(2)
	v_pk_mul_f32 v[8:9], v[8:9], v[200:201]
	s_waitcnt lgkmcnt(1)
	v_pk_mul_f32 v[4:5], v[4:5], v[196:197]
	v_pk_mul_f32 v[14:15], v[14:15], v[206:207]
	v_pk_mul_f32 v[10:11], v[10:11], v[202:203]
	v_pk_mul_f32 v[6:7], v[6:7], v[198:199]
	s_waitcnt lgkmcnt(0)
	v_pk_mul_f32 v[2:3], v[2:3], v[194:195]
	v_pk_mul_f32 v[0:1], v[0:1], v[192:193]
	v_pk_mul_f32 v[124:125], v[124:125], v[204:205]
	v_pk_mul_f32 v[120:121], v[120:121], v[200:201]
	v_pk_mul_f32 v[116:117], v[116:117], v[196:197]
	v_pk_mul_f32 v[126:127], v[126:127], v[206:207]
	v_pk_mul_f32 v[122:123], v[122:123], v[202:203]
	v_pk_mul_f32 v[118:119], v[118:119], v[198:199]
	v_pk_mul_f32 v[114:115], v[114:115], v[194:195]
	v_pk_mul_f32 v[112:113], v[112:113], v[192:193]
	v_pk_mul_f32 v[108:109], v[108:109], v[204:205]
	v_pk_mul_f32 v[104:105], v[104:105], v[200:201]
	v_pk_mul_f32 v[100:101], v[100:101], v[196:197]
	v_pk_mul_f32 v[110:111], v[110:111], v[206:207]
	v_pk_mul_f32 v[106:107], v[106:107], v[202:203]
	v_pk_mul_f32 v[102:103], v[102:103], v[198:199]
	v_pk_mul_f32 v[98:99], v[98:99], v[194:195]
	v_pk_mul_f32 v[96:97], v[96:97], v[192:193]
	v_pk_mul_f32 v[92:93], v[92:93], v[204:205]
	v_pk_mul_f32 v[88:89], v[88:89], v[200:201]
	v_pk_mul_f32 v[84:85], v[84:85], v[196:197]
	v_pk_mul_f32 v[94:95], v[94:95], v[206:207]
	v_pk_mul_f32 v[90:91], v[90:91], v[202:203]
	v_pk_mul_f32 v[86:87], v[86:87], v[198:199]
	v_pk_mul_f32 v[82:83], v[82:83], v[194:195]
	v_pk_mul_f32 v[80:81], v[80:81], v[192:193]
	v_pk_mul_f32 v[76:77], v[76:77], v[204:205]
	v_pk_mul_f32 v[72:73], v[72:73], v[200:201]
	v_pk_mul_f32 v[68:69], v[68:69], v[196:197]
	v_pk_mul_f32 v[78:79], v[78:79], v[206:207]
	v_pk_mul_f32 v[74:75], v[74:75], v[202:203]
	v_pk_mul_f32 v[70:71], v[70:71], v[198:199]
	v_pk_mul_f32 v[66:67], v[66:67], v[194:195]
	v_pk_mul_f32 v[64:65], v[64:65], v[192:193]
	v_pk_mul_f32 v[60:61], v[60:61], v[204:205]
	v_pk_mul_f32 v[56:57], v[56:57], v[200:201]
	v_pk_mul_f32 v[52:53], v[52:53], v[196:197]
	v_pk_mul_f32 v[62:63], v[62:63], v[206:207]
	v_pk_mul_f32 v[58:59], v[58:59], v[202:203]
	v_pk_mul_f32 v[54:55], v[54:55], v[198:199]
	v_pk_mul_f32 v[50:51], v[50:51], v[194:195]
	v_pk_mul_f32 v[48:49], v[48:49], v[192:193]
	v_pk_mul_f32 v[44:45], v[44:45], v[204:205]
	v_pk_mul_f32 v[40:41], v[40:41], v[200:201]
	v_pk_mul_f32 v[36:37], v[36:37], v[196:197]
	v_pk_mul_f32 v[46:47], v[46:47], v[206:207]
	v_pk_mul_f32 v[42:43], v[42:43], v[202:203]
	v_pk_mul_f32 v[38:39], v[38:39], v[198:199]
	v_pk_mul_f32 v[34:35], v[34:35], v[194:195]
	v_pk_mul_f32 v[32:33], v[32:33], v[192:193]
	v_pk_mul_f32 v[28:29], v[28:29], v[204:205]
	v_pk_mul_f32 v[24:25], v[24:25], v[200:201]
	v_pk_mul_f32 v[20:21], v[20:21], v[196:197]
	v_pk_mul_f32 v[30:31], v[30:31], v[206:207]
	v_pk_mul_f32 v[26:27], v[26:27], v[202:203]
	v_pk_mul_f32 v[22:23], v[22:23], v[198:199]
	v_pk_mul_f32 v[18:19], v[18:19], v[194:195]
	v_pk_mul_f32 v[16:17], v[16:17], v[192:193]

.Lsmf0_join:
	v_fmamk_f32 v144, v144, 0x3e0293ee, v236
	v_fmamk_f32 v145, v145, 0x3e0293ee, v236
	v_fmamk_f32 v146, v146, 0x3e0293ee, v236
	v_fmamk_f32 v147, v147, 0x3e0293ee, v236
	v_fmamk_f32 v148, v148, 0x3e0293ee, v236
	v_fmamk_f32 v149, v149, 0x3e0293ee, v236
	v_fmamk_f32 v150, v150, 0x3e0293ee, v236
	v_fmamk_f32 v151, v151, 0x3e0293ee, v236
	v_fmamk_f32 v152, v152, 0x3e0293ee, v236
	v_fmamk_f32 v153, v153, 0x3e0293ee, v236
	v_fmamk_f32 v154, v154, 0x3e0293ee, v236
	v_fmamk_f32 v155, v155, 0x3e0293ee, v236
	v_fmamk_f32 v156, v156, 0x3e0293ee, v236
	v_fmamk_f32 v157, v157, 0x3e0293ee, v236
	v_fmamk_f32 v158, v158, 0x3e0293ee, v236
	v_fmamk_f32 v159, v159, 0x3e0293ee, v236
	v_fmamk_f32 v128, v128, 0x3e0293ee, v236
	v_fmamk_f32 v129, v129, 0x3e0293ee, v236
	v_fmamk_f32 v130, v130, 0x3e0293ee, v236
	v_fmamk_f32 v131, v131, 0x3e0293ee, v236
	v_fmamk_f32 v132, v132, 0x3e0293ee, v236
	v_fmamk_f32 v133, v133, 0x3e0293ee, v236
	v_fmamk_f32 v134, v134, 0x3e0293ee, v236
	v_fmamk_f32 v135, v135, 0x3e0293ee, v236
	v_fmamk_f32 v136, v136, 0x3e0293ee, v236
	v_fmamk_f32 v137, v137, 0x3e0293ee, v236
	v_fmamk_f32 v138, v138, 0x3e0293ee, v236
	v_fmamk_f32 v139, v139, 0x3e0293ee, v236
	v_fmamk_f32 v140, v140, 0x3e0293ee, v236
	v_fmamk_f32 v141, v141, 0x3e0293ee, v236
	v_fmamk_f32 v142, v142, 0x3e0293ee, v236
	v_fmamk_f32 v192, v143, 0x3e0293ee, v236
	v_exp_f32_e32 v143, v144
	v_exp_f32_e32 v145, v145
	v_exp_f32_e32 v146, v146
	v_exp_f32_e32 v147, v147
	v_exp_f32_e32 v148, v148
	v_exp_f32_e32 v193, v128
	v_exp_f32_e32 v149, v149
	v_add_f32_e32 v128, v145, v143
	v_exp_f32_e32 v150, v150
	v_add_f32_e32 v128, v146, v128
	v_exp_f32_e32 v151, v151
	v_add_f32_e32 v128, v147, v128
	v_exp_f32_e32 v152, v152
	v_add_f32_e32 v128, v148, v128
	v_exp_f32_e32 v153, v153
	v_add_f32_e32 v128, v149, v128
	v_exp_f32_e32 v154, v154
	v_add_f32_e32 v128, v150, v128
	v_exp_f32_e32 v155, v155
	v_add_f32_e32 v128, v151, v128
	v_exp_f32_e32 v156, v156
	v_add_f32_e32 v128, v152, v128
	v_exp_f32_e32 v157, v157
	v_add_f32_e32 v128, v153, v128
	v_exp_f32_e32 v158, v158
	v_add_f32_e32 v128, v154, v128
	v_exp_f32_e32 v159, v159
	v_add_f32_e32 v128, v155, v128
	v_add_f32_e32 v128, v156, v128
	v_exp_f32_e32 v194, v129
	v_add_f32_e32 v128, v157, v128
	v_exp_f32_e32 v195, v130
	v_add_f32_e32 v128, v158, v128
	v_exp_f32_e32 v196, v131
	v_add_f32_e32 v128, v159, v128
	v_exp_f32_e32 v197, v132
	v_add_f32_e32 v128, v193, v128
	v_exp_f32_e32 v198, v133
	v_add_f32_e32 v128, v194, v128
	v_exp_f32_e32 v199, v134
	v_add_f32_e32 v128, v195, v128
	v_exp_f32_e32 v135, v135
	v_add_f32_e32 v128, v196, v128
	v_exp_f32_e32 v200, v136
	v_add_f32_e32 v128, v197, v128
	v_exp_f32_e32 v201, v137
	v_add_f32_e32 v128, v198, v128
	v_exp_f32_e32 v202, v138
	v_add_f32_e32 v128, v199, v128
	v_exp_f32_e32 v203, v139
	v_add_f32_e32 v128, v135, v128
	v_exp_f32_e32 v204, v140
	v_add_f32_e32 v128, v200, v128
	v_exp_f32_e32 v205, v141
	v_add_f32_e32 v128, v201, v128
	v_exp_f32_e32 v206, v142
	v_add_f32_e32 v128, v202, v128
	v_exp_f32_e32 v192, v192
	v_add_f32_e32 v128, v203, v128
	v_add_f32_e32 v128, v204, v128
	v_add_f32_e32 v128, v205, v128
	v_add_f32_e32 v128, v206, v128
	v_add_f32_e32 v128, v192, v128
	v_mov_b32_e32 v129, v128
	s_nop 1
	v_permlane32_swap_b32_e32 v128, v129
	v_add_f32_e32 v144, v128, v129
	v_fmac_f32_e32 v144, v232, v233
	v_cvt_pk_bf16_f32 v128, v143, v145
	v_cvt_pk_bf16_f32 v129, v146, v147
	v_cvt_pk_bf16_f32 v130, v148, v149
	v_cvt_pk_bf16_f32 v131, v150, v151
	v_cvt_pk_bf16_f32 v136, v152, v153
	v_cvt_pk_bf16_f32 v137, v154, v155
	v_cvt_pk_bf16_f32 v138, v156, v157
	v_cvt_pk_bf16_f32 v139, v158, v159
	v_cvt_pk_bf16_f32 v132, v193, v194
	v_cvt_pk_bf16_f32 v133, v195, v196
	v_cvt_pk_bf16_f32 v134, v197, v198
	v_cvt_pk_bf16_f32 v135, v199, v135
	v_cvt_pk_bf16_f32 v140, v200, v201
	v_cvt_pk_bf16_f32 v141, v202, v203
	v_cvt_pk_bf16_f32 v142, v204, v205
	v_cvt_pk_bf16_f32 v143, v206, v192
	s_nop 0
	v_permlane32_swap_b32_e32 v128, v130
	v_permlane32_swap_b32_e32 v129, v131
	v_permlane32_swap_b32_e32 v136, v138
	v_permlane32_swap_b32_e32 v137, v139
	v_permlane32_swap_b32_e32 v132, v134
	v_permlane32_swap_b32_e32 v133, v135
	v_permlane32_swap_b32_e32 v140, v142
	v_permlane32_swap_b32_e32 v141, v143
	v_lshl_add_u32 v145, s80, 15, v230
	ds_read_b64_tr_b16 v[146:147], v145 offset:0
	ds_read_b64_tr_b16 v[148:149], v145 offset:0x1000
	ds_read_b64_tr_b16 v[150:151], v145 offset:0x2000
	ds_read_b64_tr_b16 v[152:153], v145 offset:0x3000
	ds_read_b64_tr_b16 v[154:155], v145 offset:0x4000
	ds_read_b64_tr_b16 v[156:157], v145 offset:0x5000
	ds_read_b64_tr_b16 v[192:193], v145 offset:0x6000
	ds_read_b64_tr_b16 v[194:195], v145 offset:0x7000
	ds_read_b64_tr_b16 v[196:197], v145 offset:0x200
	ds_read_b64_tr_b16 v[198:199], v145 offset:0x1200
	ds_read_b64_tr_b16 v[200:201], v145 offset:0x2200
	ds_read_b64_tr_b16 v[202:203], v145 offset:0x3200
	ds_read_b64_tr_b16 v[204:205], v145 offset:0x4200
	ds_read_b64_tr_b16 v[206:207], v145 offset:0x5200
	ds_read_b64_tr_b16 v[232:233], v145 offset:0x6200
	ds_read_b64_tr_b16 v[234:235], v145 offset:0x7200
	s_waitcnt lgkmcnt(8)
	s_nop 0
	v_mfma_f32_32x32x16_bf16 v[0:15], v[128:131], v[146:149], v[0:15]
	v_mfma_f32_32x32x16_bf16 v[0:15], v[136:139], v[150:153], v[0:15]
	v_mfma_f32_32x32x16_bf16 v[0:15], v[132:135], v[154:157], v[0:15]
	v_mfma_f32_32x32x16_bf16 v[0:15], v[140:143], v[192:195], v[0:15]
	ds_read_b64_tr_b16 v[146:147], v145 offset:0x400
	ds_read_b64_tr_b16 v[148:149], v145 offset:0x1400
	ds_read_b64_tr_b16 v[150:151], v145 offset:0x2400
	ds_read_b64_tr_b16 v[152:153], v145 offset:0x3400
	ds_read_b64_tr_b16 v[154:155], v145 offset:0x4400
	ds_read_b64_tr_b16 v[156:157], v145 offset:0x5400
	ds_read_b64_tr_b16 v[192:193], v145 offset:0x6400
	ds_read_b64_tr_b16 v[194:195], v145 offset:0x7400
	s_waitcnt lgkmcnt(8)
	v_mfma_f32_32x32x16_bf16 v[112:127], v[128:131], v[196:199], v[112:127]
	v_mfma_f32_32x32x16_bf16 v[112:127], v[136:139], v[200:203], v[112:127]
	v_mfma_f32_32x32x16_bf16 v[112:127], v[132:135], v[204:207], v[112:127]
	v_mfma_f32_32x32x16_bf16 v[112:127], v[140:143], v[232:235], v[112:127]
	ds_read_b64_tr_b16 v[196:197], v145 offset:0x600
	ds_read_b64_tr_b16 v[198:199], v145 offset:0x1600
	ds_read_b64_tr_b16 v[200:201], v145 offset:0x2600
	ds_read_b64_tr_b16 v[202:203], v145 offset:0x3600
	ds_read_b64_tr_b16 v[204:205], v145 offset:0x4600
	ds_read_b64_tr_b16 v[206:207], v145 offset:0x5600
	ds_read_b64_tr_b16 v[232:233], v145 offset:0x6600
	ds_read_b64_tr_b16 v[234:235], v145 offset:0x7600
	s_waitcnt lgkmcnt(8)
	v_mfma_f32_32x32x16_bf16 v[96:111], v[128:131], v[146:149], v[96:111]
	v_mfma_f32_32x32x16_bf16 v[96:111], v[136:139], v[150:153], v[96:111]
	v_mfma_f32_32x32x16_bf16 v[96:111], v[132:135], v[154:157], v[96:111]
	v_mfma_f32_32x32x16_bf16 v[96:111], v[140:143], v[192:195], v[96:111]
	ds_read_b64_tr_b16 v[146:147], v145 offset:0x800
	ds_read_b64_tr_b16 v[148:149], v145 offset:0x1800
	ds_read_b64_tr_b16 v[150:151], v145 offset:0x2800
	ds_read_b64_tr_b16 v[152:153], v145 offset:0x3800
	ds_read_b64_tr_b16 v[154:155], v145 offset:0x4800
	ds_read_b64_tr_b16 v[156:157], v145 offset:0x5800
	ds_read_b64_tr_b16 v[192:193], v145 offset:0x6800
	ds_read_b64_tr_b16 v[194:195], v145 offset:0x7800
	s_waitcnt lgkmcnt(8)
	v_mfma_f32_32x32x16_bf16 v[80:95], v[128:131], v[196:199], v[80:95]
	v_mfma_f32_32x32x16_bf16 v[80:95], v[136:139], v[200:203], v[80:95]
	v_mfma_f32_32x32x16_bf16 v[80:95], v[132:135], v[204:207], v[80:95]
	v_mfma_f32_32x32x16_bf16 v[80:95], v[140:143], v[232:235], v[80:95]
	ds_read_b64_tr_b16 v[196:197], v145 offset:0xa00
	ds_read_b64_tr_b16 v[198:199], v145 offset:0x1a00
	ds_read_b64_tr_b16 v[200:201], v145 offset:0x2a00
	ds_read_b64_tr_b16 v[202:203], v145 offset:0x3a00
	ds_read_b64_tr_b16 v[204:205], v145 offset:0x4a00
	ds_read_b64_tr_b16 v[206:207], v145 offset:0x5a00
	ds_read_b64_tr_b16 v[232:233], v145 offset:0x6a00
	ds_read_b64_tr_b16 v[234:235], v145 offset:0x7a00
	s_waitcnt lgkmcnt(8)
	v_mfma_f32_32x32x16_bf16 v[64:79], v[128:131], v[146:149], v[64:79]
	v_mfma_f32_32x32x16_bf16 v[64:79], v[136:139], v[150:153], v[64:79]
	v_mfma_f32_32x32x16_bf16 v[64:79], v[132:135], v[154:157], v[64:79]
	v_mfma_f32_32x32x16_bf16 v[64:79], v[140:143], v[192:195], v[64:79]
	ds_read_b64_tr_b16 v[146:147], v145 offset:0xc00
	ds_read_b64_tr_b16 v[148:149], v145 offset:0x1c00
	ds_read_b64_tr_b16 v[150:151], v145 offset:0x2c00
	ds_read_b64_tr_b16 v[152:153], v145 offset:0x3c00
	ds_read_b64_tr_b16 v[154:155], v145 offset:0x4c00
	ds_read_b64_tr_b16 v[156:157], v145 offset:0x5c00
	ds_read_b64_tr_b16 v[192:193], v145 offset:0x6c00
	ds_read_b64_tr_b16 v[194:195], v145 offset:0x7c00
	s_waitcnt lgkmcnt(8)
	v_mfma_f32_32x32x16_bf16 v[48:63], v[128:131], v[196:199], v[48:63]
	v_mfma_f32_32x32x16_bf16 v[48:63], v[136:139], v[200:203], v[48:63]
	v_mfma_f32_32x32x16_bf16 v[48:63], v[132:135], v[204:207], v[48:63]
	v_mfma_f32_32x32x16_bf16 v[48:63], v[140:143], v[232:235], v[48:63]
	ds_read_b64_tr_b16 v[196:197], v145 offset:0xe00
	ds_read_b64_tr_b16 v[198:199], v145 offset:0x1e00
	ds_read_b64_tr_b16 v[200:201], v145 offset:0x2e00
	ds_read_b64_tr_b16 v[202:203], v145 offset:0x3e00
	ds_read_b64_tr_b16 v[204:205], v145 offset:0x4e00
	ds_read_b64_tr_b16 v[206:207], v145 offset:0x5e00
	ds_read_b64_tr_b16 v[232:233], v145 offset:0x6e00
	ds_read_b64_tr_b16 v[234:235], v145 offset:0x7e00
	s_waitcnt lgkmcnt(8)
	v_mfma_f32_32x32x16_bf16 v[32:47], v[128:131], v[146:149], v[32:47]
	v_mfma_f32_32x32x16_bf16 v[32:47], v[136:139], v[150:153], v[32:47]
	v_mfma_f32_32x32x16_bf16 v[32:47], v[132:135], v[154:157], v[32:47]
	v_mfma_f32_32x32x16_bf16 v[32:47], v[140:143], v[192:195], v[32:47]
	s_waitcnt lgkmcnt(0)
	v_mfma_f32_32x32x16_bf16 v[16:31], v[128:131], v[196:199], v[16:31]
	s_add_i32 s4, s80, 1
	s_cmp_lg_u32 s80, 2
	s_cselect_b32 s80, s4, 0
	s_add_i32 s4, s78, 1
	s_cmp_lg_u32 s78, 2
	s_cselect_b32 s78, s4, 0
	s_add_u32 s22, s22, 0x20000
	v_mfma_f32_32x32x16_bf16 v[16:31], v[136:139], v[200:203], v[16:31]
	s_addc_u32 s23, s23, 0
	s_add_i32 s86, s86, 1
	s_cmp_eq_u32 s22, 0x800000
	v_mfma_f32_32x32x16_bf16 v[16:31], v[132:135], v[204:207], v[16:31]
	v_mfma_f32_32x32x16_bf16 v[16:31], v[140:143], v[232:235], v[16:31]
	s_cbranch_scc1 .LBB0_914
	v_mov_b32_e32 v232, v144
	s_cmp_eq_u32 s22, 0x7e0000
	s_mov_b64 s[4:5], -1
	s_cbranch_scc1 .LBB0_903
